# plus L2 touches of each workgroup's first Fourier tile (stage 1 and stage 3) issued before the table builds
# baseline (speedup 1.0000x reference)
.LBB0_745:
	s_or_b64 exec, exec, s[4:5]
	v_and_b32_e32 v176, 0x3ff, v0
	v_and_b32_e32 v177, 1, v176
	v_lshrrev_b32_e32 v176, 3, v176
	v_lshlrev_b32_e32 v176, 6, v176
	s_lshr_b32 s98, s2, 3
	s_and_b32 s98, s98, 63
	s_and_b32 s99, s2, 7
	s_lshl_b32 s99, s99, 8
	v_add_u32_e32 v176, s98, v176
	v_lshlrev_b32_e32 v176, 11, v176
	v_lshl_add_u32 v176, v177, 7, v176
	v_add_u32_e32 v176, s99, v176
	global_load_dword v178, v176, s[20:21]
	s_cmpk_lt_i32 s2, 0x1000
	s_movk_i32 s3, 0x1000
	s_waitcnt lgkmcnt(0)
	s_barrier
	s_cbranch_scc0 .LBB0_767
	v_lshrrev_b32_e32 v3, 4, v2
	v_and_b32_e32 v5, 48, v3
	v_lshrrev_b32_e32 v6, 3, v2
	v_lshlrev_b32_e32 v24, 3, v2
	v_and_or_b32 v5, v6, 8, v5
	v_lshrrev_b32_e32 v5, 1, v5
	v_bfe_u32 v6, v24, 5, 2
	v_or_b32_e32 v5, v5, v6
	v_add_u32_e32 v14, 32, v3
	v_lshlrev_b32_e32 v75, 9, v5
	v_lshlrev_b32_e32 v5, 4, v2
	v_and_b32_e32 v7, 0x70, v14
	v_lshlrev_b32_e32 v8, 1, v14
	v_and_b32_e32 v25, 3, v4
	v_bfe_u32 v26, v2, 5, 1
	v_and_b32_e32 v81, 48, v5
	v_and_or_b32 v7, v8, 8, v7
	v_lshrrev_b32_e32 v4, 5, v2
	v_and_b32_e32 v30, 0xc0, v5
	v_bfe_u32 v5, v2, 4, 2
	v_lshlrev_b32_e32 v32, 3, v26
	v_lshlrev_b32_e32 v33, 4, v25
	v_lshrrev_b32_e32 v7, 1, v7
	v_and_or_b32 v31, v4, 4, v5
	v_or_b32_e32 v4, 48, v32
	v_and_or_b32 v46, v2, 15, v33
	v_and_b32_e32 v47, 16, v2
	v_or_b32_e32 v6, v7, v6
	v_mad_u32_u24 v4, v4, v46, v47
	v_lshlrev_b32_e32 v83, 9, v6
	v_lshlrev_b32_e32 v6, 1, v2
	v_lshlrev_b32_e32 v5, 8, v4
	v_add_u32_e32 v4, v4, v46
	v_and_b32_e32 v29, 32, v6
	v_lshlrev_b32_e32 v6, 8, v4
	v_add_u32_e32 v4, v4, v46
	v_lshlrev_b32_e32 v7, 8, v4
	v_add_u32_e32 v4, v4, v46
	v_lshlrev_b32_e32 v8, 8, v4
	v_add_u32_e32 v4, v4, v46
	v_lshlrev_b32_e32 v9, 8, v4
	v_add_u32_e32 v4, v4, v46
	v_lshlrev_b32_e32 v10, 8, v4
	v_add_u32_e32 v4, v4, v46
	v_lshlrev_b32_e32 v11, 8, v4
	v_add_u32_e32 v12, v4, v46
	v_and_b32_e32 v5, 0x3800, v5
	v_and_b32_e32 v6, 0x3f00, v6
	v_and_b32_e32 v7, 0x3e00, v7
	v_and_b32_e32 v8, 0x3f00, v8
	v_and_b32_e32 v9, 0x3c00, v9
	v_and_b32_e32 v10, 0x3f00, v10
	v_and_b32_e32 v11, 0x3e00, v11
	v_lshlrev_b32_e32 v4, 8, v12
	v_add_u32_e32 v5, s8, v5
	v_add_u32_e32 v6, s8, v6
	v_add_u32_e32 v7, s8, v7
	v_add_u32_e32 v8, s8, v8
	v_add_u32_e32 v9, s8, v9
	v_add_u32_e32 v10, s8, v10
	v_add_u32_e32 v11, s8, v11
	v_and_b32_e32 v4, 0x3f00, v4
	v_add_u32_e32 v13, s8, v4
	ds_read_b32 v4, v5
	ds_read_b32 v5, v6
	ds_read_b32 v6, v7
	ds_read_b32 v7, v8
	ds_read_b32 v8, v9
	ds_read_b32 v9, v10
	ds_read_b32 v10, v11
	ds_read_b32 v11, v13
	s_mov_b32 s0, 0x3e000000
	s_waitcnt lgkmcnt(6)
	v_pk_mul_f32 v[4:5], v[4:5], s[0:1] op_sel_hi:[1,0]
	s_add_u32 s30, s48, 0x1000
	v_cvt_pk_bf16_f32 v34, v4, v5
	s_waitcnt lgkmcnt(4)
	v_pk_mul_f32 v[4:5], v[6:7], s[0:1] op_sel_hi:[1,0]
	s_addc_u32 s31, s49, 0
	v_cvt_pk_bf16_f32 v35, v4, v5
	s_waitcnt lgkmcnt(2)
	v_pk_mul_f32 v[4:5], v[8:9], s[0:1] op_sel_hi:[1,0]
	s_add_u32 s46, s56, 0x2876000
	v_cvt_pk_bf16_f32 v36, v4, v5
	s_waitcnt lgkmcnt(0)
	v_pk_mul_f32 v[4:5], v[10:11], s[0:1] op_sel_hi:[1,0]
	s_movk_i32 s1, 0xffe9
	v_cvt_pk_bf16_f32 v37, v4, v5
	v_mad_i32_i24 v4, v46, s1, v12
	v_lshlrev_b32_e32 v5, 8, v4
	v_add_u32_e32 v4, v4, v46
	v_lshlrev_b32_e32 v6, 8, v4
	v_add_u32_e32 v4, v4, v46
	v_lshlrev_b32_e32 v7, 8, v4
	v_add_u32_e32 v4, v4, v46
	v_lshlrev_b32_e32 v8, 8, v4
	v_add_u32_e32 v4, v4, v46
	v_lshlrev_b32_e32 v9, 8, v4
	v_add_u32_e32 v4, v4, v46
	v_lshlrev_b32_e32 v10, 8, v4
	v_add_u32_e32 v4, v4, v46
	v_lshlrev_b32_e32 v11, 8, v4
	v_add_u32_e32 v12, v4, v46
	v_and_b32_e32 v5, 0x3800, v5
	v_and_b32_e32 v6, 0x3f00, v6
	v_and_b32_e32 v7, 0x3e00, v7
	v_and_b32_e32 v8, 0x3f00, v8
	v_and_b32_e32 v9, 0x3c00, v9
	v_and_b32_e32 v10, 0x3f00, v10
	v_and_b32_e32 v11, 0x3e00, v11
	v_lshlrev_b32_e32 v4, 8, v12
	v_add_u32_e32 v5, s8, v5
	v_add_u32_e32 v6, s8, v6
	v_add_u32_e32 v7, s8, v7
	v_add_u32_e32 v8, s8, v8
	v_add_u32_e32 v9, s8, v9
	v_add_u32_e32 v10, s8, v10
	v_add_u32_e32 v11, s8, v11
	v_and_b32_e32 v4, 0x3f00, v4
	v_add_u32_e32 v13, s8, v4
	ds_read_b32 v4, v5
	ds_read_b32 v5, v6
	ds_read_b32 v6, v7
	ds_read_b32 v7, v8
	ds_read_b32 v8, v9
	ds_read_b32 v9, v10
	ds_read_b32 v10, v11
	ds_read_b32 v11, v13
	s_waitcnt lgkmcnt(6)
	v_pk_mul_f32 v[4:5], v[4:5], s[0:1] op_sel_hi:[1,0]
	s_addc_u32 s47, s57, 0
	v_cvt_pk_bf16_f32 v38, v4, v5
	s_waitcnt lgkmcnt(4)
	v_pk_mul_f32 v[4:5], v[6:7], s[0:1] op_sel_hi:[1,0]
	v_lshlrev_b32_e32 v85, 6, v3
	v_cvt_pk_bf16_f32 v39, v4, v5
	s_waitcnt lgkmcnt(2)
	v_pk_mul_f32 v[4:5], v[8:9], s[0:1] op_sel_hi:[1,0]
	s_bfe_u32 s5, s2, 0x60003
	v_cvt_pk_bf16_f32 v40, v4, v5
	s_waitcnt lgkmcnt(0)
	v_pk_mul_f32 v[4:5], v[10:11], s[0:1] op_sel_hi:[1,0]
	s_lshl_b32 s48, s2, 7
	v_cvt_pk_bf16_f32 v41, v4, v5
	v_mad_i32_i24 v4, v46, s1, v12
	v_lshlrev_b32_e32 v5, 8, v4
	v_and_b32_e32 v5, 0x3800, v5
	v_add_u32_e32 v4, v4, v46
	v_add_u32_e32 v16, s8, v5
	v_lshlrev_b32_e32 v5, 8, v4
	v_and_b32_e32 v5, 0x3f00, v5
	v_add_u32_e32 v4, v4, v46
	v_add_u32_e32 v17, s8, v5
	v_lshlrev_b32_e32 v5, 8, v4
	v_and_b32_e32 v5, 0x3e00, v5
	v_add_u32_e32 v4, v4, v46
	v_add_u32_e32 v18, s8, v5
	v_lshlrev_b32_e32 v5, 8, v4
	v_add_u32_e32 v4, v4, v46
	v_and_b32_e32 v5, 0x3f00, v5
	v_add_u32_e32 v21, v4, v46
	v_add_u32_e32 v19, s8, v5
	v_lshlrev_b32_e32 v5, 8, v4
	v_lshlrev_b32_e32 v4, 8, v21
	s_ashr_i32 s1, s2, 9
	v_and_b32_e32 v4, 0x3f00, v4
	s_lshl_b32 s4, s1, 12
	v_add_u32_e32 v22, s8, v4
	v_or_b32_e32 v4, s4, v85
	v_and_b32_e32 v5, 0x3c00, v5
	v_or_b32_e32 v4, s5, v4
	v_add_u32_e32 v20, s8, v5
	v_ashrrev_i32_e32 v5, 31, v4
	v_lshlrev_b64 v[4:5], 11, v[4:5]
	s_and_b32 s6, s48, 0x380
	v_and_b32_e32 v74, 0x78, v24
	s_mov_b32 s37, 0
	v_lshl_add_u64 v[4:5], s[20:21], 0, v[4:5]
	s_lshl_b32 s36, s6, 1
	v_lshl_add_u64 v[4:5], v[4:5], 0, s[36:37]
	v_mov_b32_e32 v77, 0
	v_lshlrev_b32_e32 v76, 1, v74
	v_lshlrev_b32_e32 v87, 6, v14
	v_lshl_add_u64 v[12:13], v[4:5], 0, v[76:77]
	v_add_u32_e32 v4, s4, v87
	v_or_b32_e32 v4, s5, v4
	v_ashrrev_i32_e32 v5, 31, v4
	v_lshlrev_b64 v[4:5], 11, v[4:5]
	v_lshl_add_u64 v[4:5], s[20:21], 0, v[4:5]
	v_lshl_add_u64 v[4:5], v[4:5], 0, s[36:37]
	s_mul_hi_i32 s5, s1, 0x6000
	s_mulk_i32 s1, 0x6000
	v_lshl_add_u64 v[14:15], v[4:5], 0, v[76:77]
	v_or_b32_e32 v4, s6, v74
	s_add_u32 s4, s46, s1
	s_addc_u32 s5, s47, s5
	v_lshlrev_b32_e32 v76, 2, v4
	v_add_u32_e32 v21, v21, v46
	v_lshl_add_u64 v[8:9], s[4:5], 0, v[76:77]
	v_lshlrev_b32_e32 v23, 8, v21
	s_mov_b64 s[28:29], 0x1000
	v_add_co_u32_e32 v4, vcc, s3, v8
	v_and_b32_e32 v23, 0x3e00, v23
	v_add_lshl_u32 v21, v21, v46, 8
	v_addc_co_u32_e32 v5, vcc, 0, v9, vcc
	v_lshl_add_u64 v[8:9], v[8:9], 0, s[28:29]
	v_add_u32_e32 v23, s8, v23
	v_and_b32_e32 v21, 0x3f00, v21
	global_load_dwordx4 v[4:7], v[4:5], off
	v_add_u32_e32 v42, s8, v21
	global_load_dwordx4 v[8:11], v[8:9], off offset:16
	ds_read_b32 v16, v16
	ds_read_b32 v17, v17
	ds_read_b32 v18, v18
	ds_read_b32 v19, v19
	ds_read_b32 v20, v20
	ds_read_b32 v21, v22
	ds_read_b32 v22, v23
	ds_read_b32 v23, v42
	global_load_dwordx4 v[66:69], v[12:13], off
	global_load_dwordx4 v[70:73], v[14:15], off
	global_load_dwordx4 v[50:53], v76, s[30:31] offset:16
	global_load_dwordx4 v[54:57], v76, s[30:31]
	global_load_dwordx4 v[58:61], v76, s[4:5] offset:16
	global_load_dwordx4 v[62:65], v76, s[4:5]
	s_waitcnt lgkmcnt(6)
	v_pk_mul_f32 v[16:17], v[16:17], s[0:1] op_sel_hi:[1,0]
	v_lshrrev_b32_e32 v27, 8, v2
	v_cvt_pk_bf16_f32 v42, v16, v17
	s_waitcnt lgkmcnt(4)
	v_pk_mul_f32 v[16:17], v[18:19], s[0:1] op_sel_hi:[1,0]
	v_lshlrev_b32_e32 v28, 10, v27
	v_cvt_pk_bf16_f32 v43, v16, v17
	s_waitcnt lgkmcnt(2)
	v_pk_mul_f32 v[16:17], v[20:21], s[0:1] op_sel_hi:[1,0]
	v_and_b32_e32 v2, 31, v2
	v_cvt_pk_bf16_f32 v44, v16, v17
	s_waitcnt lgkmcnt(0)
	v_pk_mul_f32 v[16:17], v[22:23], s[0:1] op_sel_hi:[1,0]
	v_lshlrev_b32_e32 v76, 7, v27
	v_cvt_pk_bf16_f32 v45, v16, v17
	v_mad_u32_u24 v16, v46, v32, v47
	v_lshlrev_b32_e32 v17, 8, v16
	v_add_u32_e32 v16, v16, v46
	v_lshlrev_b32_e32 v18, 8, v16
	v_add_u32_e32 v16, v16, v46
	v_lshlrev_b32_e32 v19, 8, v16
	v_add_u32_e32 v16, v16, v46
	v_lshlrev_b32_e32 v20, 8, v16
	v_add_u32_e32 v16, v16, v46
	v_lshlrev_b32_e32 v12, 8, v16
	v_and_b32_e32 v12, 0x3c00, v12
	v_add_u32_e32 v21, s8, v12
	v_add_u32_e32 v12, v16, v46
	v_lshlrev_b32_e32 v13, 8, v12
	v_and_b32_e32 v13, 0x3f00, v13
	v_add_u32_e32 v12, v12, v46
	v_and_b32_e32 v17, 0x3800, v17
	v_and_b32_e32 v18, 0x3f00, v18
	v_and_b32_e32 v19, 0x3e00, v19
	v_add_u32_e32 v22, s8, v13
	v_lshlrev_b32_e32 v13, 8, v12
	v_add_lshl_u32 v12, v12, v46, 8
	v_add_u32_e32 v17, s8, v17
	v_add_u32_e32 v18, s8, v18
	v_add_u32_e32 v19, s8, v19
	v_and_b32_e32 v20, 0x3f00, v20
	v_and_b32_e32 v13, 0x3e00, v13
	v_and_b32_e32 v12, 0x3f00, v12
	v_add_u32_e32 v20, s8, v20
	v_add_u32_e32 v23, s8, v13
	v_add_u32_e32 v32, s8, v12
	ds_read_b32 v12, v17
	ds_read_b32 v13, v18
	ds_read_b32 v14, v19
	ds_read_b32 v15, v20
	ds_read_b32 v16, v21
	ds_read_b32 v17, v22
	ds_read_b32 v18, v23
	ds_read_b32 v19, v32
	s_waitcnt lgkmcnt(6)
	v_pk_mul_f32 v[12:13], v[12:13], s[0:1] op_sel_hi:[1,0]
	s_cmp_lg_u32 0, -1
	v_cvt_pk_bf16_f32 v46, v12, v13
	s_waitcnt lgkmcnt(4)
	v_pk_mul_f32 v[12:13], v[14:15], s[0:1] op_sel_hi:[1,0]
	v_lshl_or_b32 v89, v26, 2, v33
	v_cvt_pk_bf16_f32 v47, v12, v13
	s_waitcnt lgkmcnt(2)
	v_pk_mul_f32 v[12:13], v[16:17], s[0:1] op_sel_hi:[1,0]
	s_cselect_b32 s36, 0, 0
	v_cvt_pk_bf16_f32 v48, v12, v13
	s_waitcnt lgkmcnt(0)
	v_pk_mul_f32 v[12:13], v[18:19], s[0:1] op_sel_hi:[1,0]
	s_mov_b64 s[4:5], 0xecb0000
	v_or_b32_e32 v93, 1, v89
	v_or_b32_e32 v95, 2, v89
	v_or_b32_e32 v106, 3, v89
	v_or_b32_e32 v107, 8, v89
	v_or_b32_e32 v108, 9, v89
	v_or_b32_e32 v109, 10, v89
	v_or_b32_e32 v110, 11, v89
	v_cvt_pk_bf16_f32 v49, v12, v13
	v_cmp_ne_u32_e64 s[0:1], 3, v25
	v_lshl_add_u32 v91, v31, 6, 0
	v_lshlrev_b32_e32 v80, 7, v89
	v_cmp_gt_u32_e64 s[6:7], 33, v93
	v_lshlrev_b32_e32 v82, 7, v93
	v_cmp_gt_u32_e64 s[8:9], 33, v95
	v_lshlrev_b32_e32 v84, 7, v95
	v_cmp_gt_u32_e64 s[10:11], 33, v106
	v_lshlrev_b32_e32 v86, 7, v106
	v_cmp_gt_u32_e64 s[12:13], 33, v107
	v_lshlrev_b32_e32 v88, 7, v107
	v_cmp_gt_u32_e64 s[14:15], 33, v108
	s_waitcnt vmcnt(7)
	v_pk_add_f32 v[96:97], v[6:7], 1.0 op_sel_hi:[1,0]
	v_and_b32_e32 v6, 0x118, v24
	v_pk_add_f32 v[98:99], v[4:5], 1.0 op_sel_hi:[1,0]
	v_lshl_add_u64 v[4:5], s[56:57], 0, v[76:77]
	v_lshlrev_b32_e32 v76, 1, v2
	v_or3_b32 v2, v28, v29, v6
	v_lshl_add_u64 v[4:5], v[4:5], 0, v[76:77]
	v_add3_u32 v111, v30, s36, v2
	v_lshl_add_u32 v2, v3, 2, 0
	s_waitcnt vmcnt(6)
	v_pk_add_f32 v[100:101], v[10:11], 1.0 op_sel_hi:[1,0]
	v_pk_add_f32 v[102:103], v[8:9], 1.0 op_sel_hi:[1,0]
	v_lshl_add_u64 v[78:79], v[4:5], 0, s[4:5]
	v_cmp_gt_u32_e64 s[4:5], 33, v89
	v_lshlrev_b32_e32 v90, 7, v108
	v_cmp_gt_u32_e64 s[16:17], 33, v109
	v_lshlrev_b32_e32 v92, 7, v109
	v_cmp_gt_u32_e64 s[18:19], 33, v110
	v_lshlrev_b32_e32 v94, 7, v110
	s_lshl_b32 s49, s33, 7
	v_add_u32_e32 v112, 0x14080, v2
	v_lshlrev_b32_e32 v76, 1, v74
	s_mov_b32 s42, s2
	s_mov_b32 s62, 0
	s_waitcnt vmcnt(0)
	s_branch .LBB0_748

.LBB0_818:
	s_cmp_lt_i32 s58, 11
	s_cselect_b64 s[4:5], -1, 0
	s_and_b64 s[0:1], s[4:5], s[0:1]
	s_andn2_b64 vcc, exec, s[0:1]
	s_cbranch_vccnz .LBB0_843
	s_waitcnt vmcnt(0)
	v_and_b32_e32 v6, 0x3ff, v0
	s_add_u32 s100, s56, 0xecb0000
	s_addc_u32 s101, s57, 0
	s_lshr_b32 s98, s2, 3
	s_lshl_b32 s98, s98, 7
	s_and_b32 s99, s2, 7
	s_lshl_b32 s99, s99, 8
	v_lshrrev_b32_e32 v176, 2, v6
	v_and_b32_e32 v177, 1, v6
	v_add_u32_e32 v176, s98, v176
	v_lshlrev_b32_e32 v176, 11, v176
	v_lshl_add_u32 v176, v177, 7, v176
	v_add_u32_e32 v176, s99, v176
	global_load_dword v178, v176, s[100:101]
	v_cvt_f32_u32_e32 v2, v6
	s_waitcnt lgkmcnt(0)
	v_or_b32_e32 v3, 0x200, v6
	v_cvt_f32_u32_e32 v3, v3
	v_or_b32_e32 v5, 0x400, v6
	v_mul_f32_e32 v2, 0x39800000, v2
	v_cos_f32_e32 v4, v2
	v_mul_f32_e32 v2, 0x39800000, v3
	v_cos_f32_e32 v3, v2
	v_cvt_f32_u32_e32 v7, v5
	s_add_i32 s12, 0, 0x10000
	v_lshl_add_u32 v2, v6, 2, s12
	ds_write2st64_b32 v2, v4, v3 offset1:8
	v_mul_f32_e32 v3, 0x39800000, v7
	v_lshl_add_u32 v4, v5, 2, s12
	v_or_b32_e32 v5, 0x600, v6
	v_or_b32_e32 v7, 0x800, v6
	v_cos_f32_e32 v3, v3
	v_cvt_f32_u32_e32 v5, v5
	v_cvt_f32_u32_e32 v8, v7
	v_lshl_add_u32 v7, v7, 2, s12
	ds_write_b32 v4, v3
	v_mul_f32_e32 v3, 0x39800000, v5
	v_mul_f32_e32 v4, 0x39800000, v8
	v_or_b32_e32 v5, 0xa00, v6
	v_or_b32_e32 v8, 0xc00, v6
	v_cvt_f32_u32_e32 v5, v5
	v_cvt_f32_u32_e32 v9, v8
	v_cos_f32_e32 v4, v4
	v_cos_f32_e32 v3, v3
	v_mul_f32_e32 v5, 0x39800000, v5
	v_mul_f32_e32 v9, 0x39800000, v9
	v_cos_f32_e32 v5, v5
	v_cos_f32_e32 v9, v9
	s_movk_i32 s0, 0xe00
	ds_write_b32 v7, v4
	ds_write2st64_b32 v2, v3, v5 offset0:24 offset1:40
	v_lshl_add_u32 v3, v8, 2, s12
	v_cmp_gt_u32_e32 vcc, s0, v8
	ds_write_b32 v3, v9
	s_and_saveexec_b64 s[0:1], vcc
	s_cbranch_execz .LBB0_821
	v_add_u32_e32 v3, 0xe00, v6
	v_cvt_f32_u32_e32 v3, v3
	v_mul_f32_e32 v3, 0x39800000, v3
	v_cos_f32_e32 v3, v3
	ds_write_b32 v2, v3 offset:14336
